# waves 1..7 warm the XCD L2 with the next GEMM's first weight slabs while wave 0 runs the seam protocol (7 seams)
# baseline (speedup 1.0000x reference)
.LBB0_597:
	s_waitcnt vmcnt(0)
	v_readfirstlane_b32 s0, v194
	v_readlane_b32 s88, v242, 20
	s_cmp_gt_u32 s0, 63
	v_readlane_b32 s89, v242, 21
	s_barrier
	s_cbranch_scc0 .Lbpf_0
	s_lshr_b32 s3, s2, 6
	s_lshl_b32 s3, s3, 19
	s_add_u32 s4, s92, 0x600000
	s_addc_u32 s5, s93, 0
	s_add_u32 s4, s4, s3
	s_addc_u32 s5, s5, 0
	v_lshrrev_b32_e32 v244, 1, v194
	v_lshlrev_b32_e32 v244, 11, v244
	v_and_b32_e32 v243, 1, v194
	v_lshl_or_b32 v244, v243, 7, v244
	global_load_dword v243, v244, s[4:5]
	global_load_dword v243, v244, s[4:5] offset:256
.Lbpf_0:
	s_cmp_gt_u32 s0, 63
	s_cbranch_scc1 .LBB0_651
	v_mbcnt_lo_u32_b32 v0, -1, 0
	v_mbcnt_hi_u32_b32 v0, -1, v0
	s_nop 0
	v_cmp_eq_u32_e32 vcc, 0, v0
	s_and_saveexec_b64 s[0:1], vcc
	s_cbranch_execz .LBB0_650
	s_add_i32 s3, 0, 0x23ff0
	v_mov_b32_e32 v0, s3
	s_waitcnt vmcnt(0) expcnt(0) lgkmcnt(0)
	ds_read_b32 v2, v0
	s_add_i32 s3, 0, 0x23ff4
	v_mov_b32_e32 v0, s3
	ds_read_b32 v0, v0
	s_waitcnt lgkmcnt(1)
	v_cmp_ne_u32_e32 vcc, 0, v2
	s_cbranch_vccnz .LBB0_614
	s_mov_b32 s3, 1
	v_mov_b32_e32 v16, 0
	s_branch .LBB0_602

.LBB0_689:
	s_waitcnt vmcnt(0)
	v_readfirstlane_b32 s3, v194
	s_cmp_gt_u32 s3, 63
	s_waitcnt lgkmcnt(0)
	s_barrier
	s_cbranch_scc0 .Lbpf_1
	s_lshr_b32 s8, s2, 6
	s_lshl_b32 s8, s8, 19
	s_add_u32 s4, s92, 0xd000000
	s_addc_u32 s5, s93, 0
	s_add_u32 s4, s4, s8
	s_addc_u32 s5, s5, 0
	v_lshrrev_b32_e32 v244, 1, v194
	v_lshlrev_b32_e32 v244, 11, v244
	v_and_b32_e32 v243, 1, v194
	v_lshl_or_b32 v244, v243, 7, v244
	global_load_dword v243, v244, s[4:5]
	global_load_dword v243, v244, s[4:5] offset:256
.Lbpf_1:
	s_cmp_gt_u32 s3, 63
	s_cbranch_scc1 .LBB0_743
	v_mbcnt_lo_u32_b32 v0, -1, 0
	v_mbcnt_hi_u32_b32 v0, -1, v0
	s_nop 0
	v_cmp_eq_u32_e32 vcc, 0, v0
	s_and_saveexec_b64 s[6:7], vcc
	s_cbranch_execz .LBB0_742
	v_mov_b32_e32 v20, 0x23ff0
	s_waitcnt vmcnt(0) lgkmcnt(0)
	ds_read_b128 v[20:23], v20
	s_waitcnt lgkmcnt(0)
	v_readfirstlane_b32 s3, v22
	s_nop 0
	s_cmp_eq_u32 s3, 0
	s_cbranch_scc1 .Lfb_slow_2
	v_readfirstlane_b32 s8, v20
	s_cmp_eq_u32 s8, 32
	s_cbranch_scc0 .Lfb_xcd_2
	buffer_inv sc1
	s_getreg_b32 s3, hwreg(HW_REG_XCC_ID, 0, 4)
	s_and_b32 s3, s3, 7
	s_lshl_b32 s3, s3, 8
	s_add_u32 s3, s3, 0x3600
	s_add_u32 s4, s92, 0x510000
	s_addc_u32 s5, s93, 0
	v_mov_b32_e32 v27, 1
	s_bfe_u32 s8, s2, 0x30003
	s_lshl_b32 s8, s8, 2
	s_add_u32 s8, s8, s3
	s_add_u32 s8, s8, 0xc0
	v_mov_b32_e32 v26, s8
	global_atomic_add v26, v27, s[4:5]
	s_bfe_u32 s8, s2, 0x30003
	s_lshl_b32 s8, s8, 2
	s_add_u32 s8, s8, s3
	s_add_u32 s8, s8, 0xc0
	v_mov_b32_e32 v26, s8
	v_mov_b32_e32 v25, 4
	s_mov_b32 s8, 0
	s_branch .Lfb_spin_2

.LBB0_772:
	s_waitcnt vmcnt(0)
	v_readfirstlane_b32 s0, v194
	s_cmp_gt_u32 s0, 63
	s_waitcnt vmcnt(0)
	s_barrier
	s_cbranch_scc0 .Lbpf_2
	s_lshr_b32 s8, s2, 6
	s_lshl_b32 s8, s8, 21
	s_add_u32 s4, s92, 0xd800000
	s_addc_u32 s5, s93, 0
	s_add_u32 s4, s4, s8
	s_addc_u32 s5, s5, 0
	v_lshrrev_b32_e32 v244, 1, v194
	v_lshlrev_b32_e32 v244, 13, v244
	v_and_b32_e32 v243, 1, v194
	v_lshl_or_b32 v244, v243, 7, v244
	global_load_dword v243, v244, s[4:5]
	global_load_dword v243, v244, s[4:5] offset:256
.Lbpf_2:
	s_cmp_gt_u32 s0, 63
	s_cbranch_scc1 .LBB0_826
	v_mbcnt_lo_u32_b32 v0, -1, 0
	v_mbcnt_hi_u32_b32 v0, -1, v0
	s_nop 0
	v_cmp_eq_u32_e32 vcc, 0, v0
	s_and_saveexec_b64 s[0:1], vcc
	s_cbranch_execz .LBB0_825
	v_mov_b32_e32 v20, 0x23ff0
	s_waitcnt vmcnt(0) lgkmcnt(0)
	ds_read_b128 v[20:23], v20
	s_waitcnt lgkmcnt(0)
	v_readfirstlane_b32 s3, v22
	s_nop 0
	s_cmp_eq_u32 s3, 0
	s_cbranch_scc1 .Lfb_slow_3
	v_readfirstlane_b32 s8, v20
	s_cmp_eq_u32 s8, 32
	s_cbranch_scc0 .Lfb_xcd_3
	buffer_inv sc1
	s_getreg_b32 s3, hwreg(HW_REG_XCC_ID, 0, 4)
	s_and_b32 s3, s3, 7
	s_lshl_b32 s3, s3, 8
	s_add_u32 s3, s3, 0x3600
	s_add_u32 s4, s92, 0x510000
	s_addc_u32 s5, s93, 0
	v_mov_b32_e32 v27, 1
	s_bfe_u32 s8, s2, 0x30003
	s_lshl_b32 s8, s8, 2
	s_add_u32 s8, s8, s3
	s_add_u32 s8, s8, 0xc0
	v_mov_b32_e32 v26, s8
	global_atomic_add v26, v27, s[4:5]
	s_bfe_u32 s8, s2, 0x30003
	s_lshl_b32 s8, s8, 2
	s_add_u32 s8, s8, s3
	s_add_u32 s8, s8, 0xc0
	v_mov_b32_e32 v26, s8
	v_mov_b32_e32 v25, 8
	s_mov_b32 s8, 0
	s_branch .Lfb_spin_3

.LBB0_864:
	s_waitcnt vmcnt(0)
	v_readfirstlane_b32 s3, v194
	s_cmp_gt_u32 s3, 63
	s_waitcnt lgkmcnt(0)
	s_barrier
	s_cbranch_scc0 .Lbpf_3
	s_lshr_b32 s8, s2, 6
	s_lshl_b32 s8, s8, 19
	s_add_u32 s4, s92, 0xe000000
	s_addc_u32 s5, s93, 0
	s_add_u32 s4, s4, s8
	s_addc_u32 s5, s5, 0
	v_lshrrev_b32_e32 v244, 1, v194
	v_lshlrev_b32_e32 v244, 11, v244
	v_and_b32_e32 v243, 1, v194
	v_lshl_or_b32 v244, v243, 7, v244
	global_load_dword v243, v244, s[4:5]
	global_load_dword v243, v244, s[4:5] offset:256
.Lbpf_3:
	s_cmp_gt_u32 s3, 63
	s_cbranch_scc1 .LBB0_918
	v_mbcnt_lo_u32_b32 v0, -1, 0
	v_mbcnt_hi_u32_b32 v0, -1, v0
	s_nop 0
	v_cmp_eq_u32_e32 vcc, 0, v0
	s_and_saveexec_b64 s[6:7], vcc
	s_cbranch_execz .LBB0_917
	v_mov_b32_e32 v20, 0x23ff0
	s_waitcnt vmcnt(0) lgkmcnt(0)
	ds_read_b128 v[20:23], v20
	s_waitcnt lgkmcnt(0)
	v_readfirstlane_b32 s3, v22
	s_nop 0
	s_cmp_eq_u32 s3, 0
	s_cbranch_scc1 .Lfb_slow_4
	buffer_inv sc1
	v_add_u32_e32 v23, 1, v23
	v_mov_b32_e32 v24, 0x23ffc
	ds_write_b32 v24, v23
	v_mul_lo_u32 v25, v23, v20
	s_getreg_b32 s3, hwreg(HW_REG_XCC_ID, 0, 4)
	s_and_b32 s3, s3, 7
	s_lshl_b32 s3, s3, 8
	s_add_u32 s3, s3, 0x3680
	s_add_u32 s4, s92, 0x510000
	s_addc_u32 s5, s93, 0
	v_mov_b32_e32 v26, s3
	v_mov_b32_e32 v27, 1
	global_atomic_add v26, v27, s[4:5]
	s_mov_b32 s8, 0

.LBB0_1157:
	s_waitcnt vmcnt(0)
	v_readfirstlane_b32 s0, v194
	v_readlane_b32 s62, v241, 5
	s_cmp_gt_u32 s0, 63
	v_readlane_b32 s63, v241, 6
	s_waitcnt lgkmcnt(0)
	s_barrier
	s_cbranch_scc0 .Lbpf_4
	s_lshr_b32 s8, s2, 6
	s_lshl_b32 s8, s8, 19
	s_add_u32 s4, s92, 0xe600000
	s_addc_u32 s5, s93, 0
	s_add_u32 s4, s4, s8
	s_addc_u32 s5, s5, 0
	v_lshrrev_b32_e32 v244, 1, v194
	v_lshlrev_b32_e32 v244, 11, v244
	v_and_b32_e32 v243, 1, v194
	v_lshl_or_b32 v244, v243, 7, v244
	global_load_dword v243, v244, s[4:5]
	global_load_dword v243, v244, s[4:5] offset:256
.Lbpf_4:
	s_cmp_gt_u32 s0, 63
	s_cbranch_scc1 .LBB0_1211
	v_mbcnt_lo_u32_b32 v0, -1, 0
	v_mbcnt_hi_u32_b32 v0, -1, v0
	s_nop 0
	v_cmp_eq_u32_e32 vcc, 0, v0
	s_and_saveexec_b64 s[0:1], vcc
	s_cbranch_execz .LBB0_1210
	v_mov_b32_e32 v20, 0x23ff0
	s_waitcnt vmcnt(0) lgkmcnt(0)
	ds_read_b128 v[20:23], v20
	s_waitcnt lgkmcnt(0)
	v_readfirstlane_b32 s3, v22
	s_nop 0
	s_cmp_eq_u32 s3, 0
	s_cbranch_scc1 .Lfb_slow_6
	v_readfirstlane_b32 s8, v20
	s_cmp_eq_u32 s8, 32
	s_cbranch_scc0 .Lfb_xcd_6
	buffer_inv sc1
	s_getreg_b32 s3, hwreg(HW_REG_XCC_ID, 0, 4)
	s_and_b32 s3, s3, 7
	s_lshl_b32 s3, s3, 8
	s_add_u32 s3, s3, 0x3600
	s_add_u32 s4, s92, 0x510000
	s_addc_u32 s5, s93, 0
	v_mov_b32_e32 v27, 1
	s_bfe_u32 s8, s2, 0x20003
	s_lshl_b32 s8, s8, 2
	s_add_u32 s8, s8, s3
	s_add_u32 s8, s8, 0x40
	v_mov_b32_e32 v26, s8
	global_atomic_add v26, v27, s[4:5]
	s_mov_b32 s8, s3
	s_add_u32 s8, s8, 0x50
	v_mov_b32_e32 v26, s8
	global_atomic_add v26, v27, s[4:5]
	s_bfe_u32 s8, s2, 0x30003
	s_bitcmp1_b32 s2, 5
	s_cbranch_scc0 .Lfb_aw_6
	s_xor_b32 s8, s8, 7

.LBB0_1249:
	s_waitcnt vmcnt(0)
	v_readfirstlane_b32 s3, v194
	s_cmp_gt_u32 s3, 63
	s_waitcnt lgkmcnt(0)
	s_barrier
	s_cbranch_scc0 .Lbpf_5
	s_lshr_b32 s8, s2, 6
	s_lshl_b32 s8, s8, 19
	s_add_u32 s4, s92, 0xe800000
	s_addc_u32 s5, s93, 0
	s_add_u32 s4, s4, s8
	s_addc_u32 s5, s5, 0
	v_lshrrev_b32_e32 v244, 1, v194
	v_lshlrev_b32_e32 v244, 11, v244
	v_and_b32_e32 v243, 1, v194
	v_lshl_or_b32 v244, v243, 7, v244
	global_load_dword v243, v244, s[4:5]
	global_load_dword v243, v244, s[4:5] offset:256
.Lbpf_5:
	s_cmp_gt_u32 s3, 63
	s_cbranch_scc1 .LBB0_1303
	v_mbcnt_lo_u32_b32 v0, -1, 0
	v_mbcnt_hi_u32_b32 v0, -1, v0
	s_nop 0
	v_cmp_eq_u32_e32 vcc, 0, v0
	s_and_saveexec_b64 s[6:7], vcc
	s_cbranch_execz .LBB0_1302
	v_mov_b32_e32 v20, 0x23ff0
	s_waitcnt vmcnt(0) lgkmcnt(0)
	ds_read_b128 v[20:23], v20
	s_waitcnt lgkmcnt(0)
	v_readfirstlane_b32 s3, v22
	s_nop 0
	s_cmp_eq_u32 s3, 0
	s_cbranch_scc1 .Lfb_slow_7
	v_readfirstlane_b32 s8, v20
	s_cmp_eq_u32 s8, 32
	s_cbranch_scc0 .Lfb_xcd_7
	buffer_inv sc1
	s_getreg_b32 s3, hwreg(HW_REG_XCC_ID, 0, 4)
	s_and_b32 s3, s3, 7
	s_lshl_b32 s3, s3, 8
	s_add_u32 s3, s3, 0x3600
	s_add_u32 s4, s92, 0x510000
	s_addc_u32 s5, s93, 0
	v_mov_b32_e32 v27, 1
	s_bfe_u32 s8, s2, 0x30003
	s_lshl_b32 s8, s8, 2
	s_add_u32 s8, s8, s3
	s_add_u32 s8, s8, 0xc0
	v_mov_b32_e32 v26, s8
	global_atomic_add v26, v27, s[4:5]
	s_mov_b32 s8, s3
	s_add_u32 s8, s8, 0x54
	v_mov_b32_e32 v26, s8
	global_atomic_add v26, v27, s[4:5]
	s_bfe_u32 s8, s2, 0x30003
	s_lshl_b32 s8, s8, 2
	s_add_u32 s8, s8, s3
	s_add_u32 s8, s8, 0xc0
	v_mov_b32_e32 v26, s8
	v_mov_b32_e32 v25, 12
	s_mov_b32 s8, 0

.LBB0_1332:
	s_waitcnt vmcnt(0)
	v_readfirstlane_b32 s0, v194
	s_cmp_gt_u32 s0, 63
	s_waitcnt vmcnt(0)
	s_barrier
	s_cbranch_scc0 .Lbpf_6
	s_lshr_b32 s8, s2, 6
	s_lshl_b32 s8, s8, 21
	s_add_u32 s4, s92, 0xf000000
	s_addc_u32 s5, s93, 0
	s_add_u32 s4, s4, s8
	s_addc_u32 s5, s5, 0
	v_lshrrev_b32_e32 v244, 1, v194
	v_lshlrev_b32_e32 v244, 13, v244
	v_and_b32_e32 v243, 1, v194
	v_lshl_or_b32 v244, v243, 7, v244
	global_load_dword v243, v244, s[4:5]
	global_load_dword v243, v244, s[4:5] offset:256
.Lbpf_6:
	s_cmp_gt_u32 s0, 63
	s_cbranch_scc1 .LBB0_1386
	v_mbcnt_lo_u32_b32 v0, -1, 0
	v_mbcnt_hi_u32_b32 v0, -1, v0
	s_nop 0
	v_cmp_eq_u32_e32 vcc, 0, v0
	s_and_saveexec_b64 s[0:1], vcc
	s_cbranch_execz .LBB0_1385
	v_mov_b32_e32 v20, 0x23ff0
	s_waitcnt vmcnt(0) lgkmcnt(0)
	ds_read_b128 v[20:23], v20
	s_waitcnt lgkmcnt(0)
	v_readfirstlane_b32 s3, v22
	s_nop 0
	s_cmp_eq_u32 s3, 0
	s_cbranch_scc1 .Lfb_slow_8
	v_readfirstlane_b32 s8, v20
	s_cmp_eq_u32 s8, 32
	s_cbranch_scc0 .Lfb_xcd_8
	buffer_inv sc1
	s_getreg_b32 s3, hwreg(HW_REG_XCC_ID, 0, 4)
	s_and_b32 s3, s3, 7
	s_lshl_b32 s3, s3, 8
	s_add_u32 s3, s3, 0x3600
	s_add_u32 s4, s92, 0x510000
	s_addc_u32 s5, s93, 0
	v_mov_b32_e32 v27, 1
	s_bfe_u32 s8, s2, 0x30003
	s_lshl_b32 s8, s8, 2
	s_add_u32 s8, s8, s3
	s_add_u32 s8, s8, 0xc0
	v_mov_b32_e32 v26, s8
	global_atomic_add v26, v27, s[4:5]
	s_bfe_u32 s8, s2, 0x30003
	s_lshl_b32 s8, s8, 2
	s_add_u32 s8, s8, s3
	s_add_u32 s8, s8, 0xc0
	v_mov_b32_e32 v26, s8
	v_mov_b32_e32 v25, 16
	s_mov_b32 s8, 0

	.amdhsa_kernel _Z8yoco_fwd4Args
		.amdhsa_group_segment_fixed_size 0
		.amdhsa_private_segment_fixed_size 0
		.amdhsa_kernarg_size 440
		.amdhsa_user_sgpr_count 2
		.amdhsa_user_sgpr_dispatch_ptr 0
		.amdhsa_user_sgpr_queue_ptr 0
		.amdhsa_user_sgpr_kernarg_segment_ptr 1
		.amdhsa_user_sgpr_dispatch_id 0
		.amdhsa_user_sgpr_kernarg_preload_length 0
		.amdhsa_user_sgpr_kernarg_preload_offset 0
		.amdhsa_user_sgpr_private_segment_size 0
		.amdhsa_uses_dynamic_stack 0
		.amdhsa_enable_private_segment 0
		.amdhsa_system_sgpr_workgroup_id_x 1
		.amdhsa_system_sgpr_workgroup_id_y 0
		.amdhsa_system_sgpr_workgroup_id_z 0
		.amdhsa_system_sgpr_workgroup_info 0
		.amdhsa_system_vgpr_workitem_id 2
		.amdhsa_next_free_vgpr 245
		.amdhsa_next_free_sgpr 98
		.amdhsa_accum_offset 248
		.amdhsa_reserve_vcc 1
		.amdhsa_float_round_mode_32 0
		.amdhsa_float_round_mode_16_64 0
		.amdhsa_float_denorm_mode_32 3
		.amdhsa_float_denorm_mode_16_64 3
		.amdhsa_dx10_clamp 1
		.amdhsa_ieee_mode 1
		.amdhsa_fp16_overflow 0
		.amdhsa_tg_split 0
		.amdhsa_exception_fp_ieee_invalid_op 0
		.amdhsa_exception_fp_denorm_src 0
		.amdhsa_exception_fp_ieee_div_zero 0
		.amdhsa_exception_fp_ieee_overflow 0
		.amdhsa_exception_fp_ieee_underflow 0
		.amdhsa_exception_fp_ieee_inexact 0
		.amdhsa_exception_int_div_zero 0
	.end_amdhsa_kernel

amdhsa.kernels:
  - .agpr_count:     0
    .args:
      - .offset:         0
        .size:           184
        .value_kind:     by_value
      - .offset:         184
        .size:           4
        .value_kind:     hidden_block_count_x
      - .offset:         188
        .size:           4
        .value_kind:     hidden_block_count_y
      - .offset:         192
        .size:           4
        .value_kind:     hidden_block_count_z
      - .offset:         196
        .size:           2
        .value_kind:     hidden_group_size_x
      - .offset:         198
        .size:           2
        .value_kind:     hidden_group_size_y
      - .offset:         200
        .size:           2
        .value_kind:     hidden_group_size_z
      - .offset:         202
        .size:           2
        .value_kind:     hidden_remainder_x
      - .offset:         204
        .size:           2
        .value_kind:     hidden_remainder_y
      - .offset:         206
        .size:           2
        .value_kind:     hidden_remainder_z
      - .offset:         224
        .size:           8
        .value_kind:     hidden_global_offset_x
      - .offset:         232
        .size:           8
        .value_kind:     hidden_global_offset_y
      - .offset:         240
        .size:           8
        .value_kind:     hidden_global_offset_z
      - .offset:         248
        .size:           2
        .value_kind:     hidden_grid_dims
      - .offset:         272
        .size:           8
        .value_kind:     hidden_multigrid_sync_arg
      - .offset:         304
        .size:           4
        .value_kind:     hidden_dynamic_lds_size
    .group_segment_fixed_size: 0
    .kernarg_segment_align: 8
    .kernarg_segment_size: 440
    .language:       OpenCL C
    .language_version:
      - 2
      - 0
    .max_flat_workgroup_size: 512
    .name:           _Z8yoco_fwd4Args
    .private_segment_fixed_size: 0
    .sgpr_count:     104
    .sgpr_spill_count: 152
    .symbol:         _Z8yoco_fwd4Args.kd
    .uniform_work_group_size: 1
    .uses_dynamic_stack: false
    .vgpr_count:     245
    .vgpr_spill_count: 0
    .wavefront_size: 64
